# RMSNorm phases: 64-lane sum of squares via DPP + permlane swaps (same addition tree) instead of six ds_bpermute round trips
# speedup vs baseline: 1.0009x; 1.0008x over previous
.LBB0_1407:
	s_add_i32 s6, s34, s36
	s_add_i32 s28, s6, 4
	s_ashr_i32 s29, s28, 31
	s_lshl_b64 s[8:9], s[28:29], 12
	v_lshl_add_u64 v[18:19], v[84:85], 0, s[8:9]
	global_load_dwordx4 v[78:81], v[18:19], off
	global_load_dwordx4 v[74:77], v[18:19], off offset:1024
	global_load_dwordx4 v[66:69], v[18:19], off offset:3072
	global_load_dwordx4 v[70:73], v[18:19], off offset:2048
	s_add_i32 s26, s6, 5
	s_add_i32 s22, s6, 6
	s_add_i32 s18, s6, 7
	s_ashr_i32 s27, s26, 31
	s_ashr_i32 s23, s22, 31
	s_ashr_i32 s19, s18, 31
	s_lshl_b64 s[24:25], s[26:27], 12
	s_lshl_b64 s[20:21], s[22:23], 12
	s_lshl_b64 s[16:17], s[18:19], 12
	v_lshl_add_u64 v[18:19], v[84:85], 0, s[24:25]
	v_lshl_add_u64 v[20:21], v[84:85], 0, s[20:21]
	v_lshl_add_u64 v[108:109], v[84:85], 0, s[16:17]
	global_load_dwordx4 v[62:65], v[18:19], off
	global_load_dwordx4 v[58:61], v[18:19], off offset:1024
	global_load_dwordx4 v[54:57], v[18:19], off offset:2048
	global_load_dwordx4 v[50:53], v[18:19], off offset:3072
	global_load_dwordx4 v[46:49], v[20:21], off
	global_load_dwordx4 v[42:45], v[20:21], off offset:1024
	global_load_dwordx4 v[38:41], v[20:21], off offset:2048
	global_load_dwordx4 v[34:37], v[20:21], off offset:3072
	global_load_dwordx4 v[30:33], v[108:109], off
	global_load_dwordx4 v[26:29], v[108:109], off offset:1024
	global_load_dwordx4 v[22:25], v[108:109], off offset:2048
	s_nop 0
	global_load_dwordx4 v[18:21], v[108:109], off offset:3072
	s_and_b64 s[6:7], exec, s[66:67]
	s_lshl_b64 s[28:29], s[28:29], 11
	s_mov_b64 s[30:31], -1
	s_waitcnt vmcnt(15)
	v_pk_mul_f32 v[108:109], v[80:81], v[80:81]
	v_pk_mul_f32 v[110:111], v[78:79], v[78:79]
	s_waitcnt vmcnt(14)
	v_pk_mul_f32 v[112:113], v[76:77], v[76:77]
	v_pk_mul_f32 v[120:121], v[74:75], v[74:75]
	v_pk_mov_b32 v[124:125], v[110:111], v[108:109] op_sel:[1,0]
	v_mov_b32_e32 v111, v109
	v_pk_mov_b32 v[108:109], v[120:121], v[112:113] op_sel:[1,0]
	v_mov_b32_e32 v121, v113
	s_waitcnt vmcnt(12)
	v_mul_f32_e32 v0, v71, v71
	v_mul_f32_e32 v122, v73, v73
	v_pk_add_f32 v[110:111], v[124:125], v[110:111]
	v_pk_add_f32 v[108:109], v[108:109], v[120:121]
	v_mul_f32_e32 v119, v66, v66
	v_mul_f32_e32 v126, v67, v67
	v_mul_f32_e32 v127, v68, v68
	v_mul_f32_e32 v128, v69, v69
	v_pk_fma_f32 v[112:113], v[70:71], v[70:71], v[0:1] op_sel_hi:[1,1,0]
	v_pk_fma_f32 v[122:123], v[72:73], v[72:73], v[122:123] op_sel_hi:[1,1,0]
	v_pk_add_f32 v[110:111], v[110:111], v[110:111] op_sel:[0,1] op_sel_hi:[1,0]
	v_pk_add_f32 v[108:109], v[108:109], v[108:109] op_sel:[0,1] op_sel_hi:[1,0]
	v_mov_b32_e32 v113, v127
	v_mov_b32_e32 v123, v128
	v_mov_b32_e32 v111, v119
	v_mov_b32_e32 v109, v126
	v_pk_add_f32 v[112:113], v[112:113], v[122:123]
	v_pk_add_f32 v[108:109], v[110:111], v[108:109]
	s_nop 0
	v_pk_add_f32 v[108:109], v[108:109], v[112:113]
	s_nop 0
	v_add_f32_e32 v0, v108, v109
	s_nop 1
	v_add_f32_dpp v0, v0, v0 quad_perm:[1,0,3,2] row_mask:0xf bank_mask:0xf
	s_nop 1
	v_add_f32_dpp v0, v0, v0 quad_perm:[2,3,0,1] row_mask:0xf bank_mask:0xf
	s_nop 1
	v_add_f32_dpp v0, v0, v0 row_half_mirror row_mask:0xf bank_mask:0xf
	s_nop 1
	v_add_f32_dpp v0, v0, v0 row_mirror row_mask:0xf bank_mask:0xf
	v_mov_b32_e32 v108, v0
	s_nop 1
	v_permlane16_swap_b32 v108, v0
	s_nop 0
	v_add_f32_e32 v0, v108, v0
	v_mov_b32_e32 v108, v0
	s_nop 1
	v_permlane32_swap_b32 v108, v0
	s_nop 0
	v_add_f32_e32 v0, v108, v0
	v_fmamk_f32 v0, v0, 0x3a800000, v177
	v_mul_f32_e32 v108, 0x4b800000, v0
	v_cmp_gt_f32_e32 vcc, s52, v0
	s_nop 1
	v_cndmask_b32_e32 v0, v0, v108, vcc
	v_rsq_f32_e32 v0, v0
	v_lshl_add_u64 v[108:109], v[86:87], 0, s[28:29]
	v_mul_f32_e32 v110, 0x45800000, v0
	v_cndmask_b32_e32 v112, v0, v110, vcc
	v_pk_mul_f32 v[78:79], v[112:113], v[78:79] op_sel_hi:[0,1]
	v_pk_mul_f32 v[80:81], v[112:113], v[80:81] op_sel_hi:[0,1]
	v_pk_fma_f32 v[80:81], v[92:93], v[80:81], v[4:5]
	v_pk_fma_f32 v[78:79], v[94:95], v[78:79], v[2:3]
	s_mov_b64 vcc, s[6:7]
	s_cbranch_vccz .LBB0_1409
	v_cvt_pk_bf16_f32 v110, v78, v79
	v_cvt_pk_bf16_f32 v111, v80, v81
	global_store_dwordx2 v[108:109], v[110:111], off
	s_mov_b64 s[30:31], 0

.LBB0_1423:
	s_waitcnt vmcnt(11)
	s_nop 0
	v_pk_mul_f32 v[66:67], v[64:65], v[64:65]
	v_pk_mul_f32 v[68:69], v[62:63], v[62:63]
	s_waitcnt vmcnt(8)
	v_mul_f32_e32 v0, v50, v50
	v_pk_mov_b32 v[70:71], v[68:69], v[66:67] op_sel:[1,0]
	v_mov_b32_e32 v69, v67
	v_pk_add_f32 v[66:67], v[70:71], v[68:69]
	v_pk_mul_f32 v[68:69], v[60:61], v[60:61]
	v_pk_mul_f32 v[70:71], v[58:59], v[58:59]
	v_pk_add_f32 v[66:67], v[66:67], v[66:67] op_sel:[0,1] op_sel_hi:[1,0]
	v_pk_mov_b32 v[72:73], v[70:71], v[68:69] op_sel:[1,0]
	v_mov_b32_e32 v71, v69
	v_pk_add_f32 v[68:69], v[72:73], v[70:71]
	v_mul_f32_e32 v70, v51, v51
	v_pk_add_f32 v[68:69], v[68:69], v[68:69] op_sel:[0,1] op_sel_hi:[1,0]
	v_mov_b32_e32 v67, v0
	v_mov_b32_e32 v69, v70
	v_mul_f32_e32 v0, v55, v55
	v_mul_f32_e32 v71, v52, v52
	v_pk_add_f32 v[66:67], v[66:67], v[68:69]
	v_pk_fma_f32 v[68:69], v[54:55], v[54:55], v[0:1] op_sel_hi:[1,1,0]
	v_mul_f32_e32 v0, v57, v57
	v_mul_f32_e32 v72, v53, v53
	v_mov_b32_e32 v69, v71
	v_pk_fma_f32 v[70:71], v[56:57], v[56:57], v[0:1] op_sel_hi:[1,1,0]
	s_lshl_b64 s[26:27], s[26:27], 11
	v_mov_b32_e32 v71, v72
	v_pk_add_f32 v[68:69], v[68:69], v[70:71]
	s_and_b64 vcc, exec, s[6:7]
	v_pk_add_f32 v[66:67], v[66:67], v[68:69]
	s_nop 0
	v_add_f32_e32 v0, v66, v67
	s_nop 1
	v_add_f32_dpp v0, v0, v0 quad_perm:[1,0,3,2] row_mask:0xf bank_mask:0xf
	s_nop 1
	v_add_f32_dpp v0, v0, v0 quad_perm:[2,3,0,1] row_mask:0xf bank_mask:0xf
	s_nop 1
	v_add_f32_dpp v0, v0, v0 row_half_mirror row_mask:0xf bank_mask:0xf
	s_nop 1
	v_add_f32_dpp v0, v0, v0 row_mirror row_mask:0xf bank_mask:0xf
	v_mov_b32_e32 v66, v0
	s_nop 1
	v_permlane16_swap_b32 v66, v0
	s_nop 0
	v_add_f32_e32 v0, v66, v0
	v_mov_b32_e32 v66, v0
	s_nop 1
	v_permlane32_swap_b32 v66, v0
	s_nop 0
	v_add_f32_e32 v0, v66, v0
	v_fmamk_f32 v0, v0, 0x3a800000, v177
	v_mul_f32_e32 v66, 0x4b800000, v0
	v_cmp_gt_f32_e64 s[8:9], s52, v0
	s_nop 1
	v_cndmask_b32_e64 v0, v0, v66, s[8:9]
	v_rsq_f32_e32 v0, v0
	v_lshl_add_u64 v[66:67], v[86:87], 0, s[26:27]
	v_mul_f32_e32 v68, 0x45800000, v0
	v_cndmask_b32_e64 v70, v0, v68, s[8:9]
	v_pk_mul_f32 v[62:63], v[70:71], v[62:63] op_sel_hi:[0,1]
	v_pk_mul_f32 v[64:65], v[70:71], v[64:65] op_sel_hi:[0,1]
	v_pk_fma_f32 v[64:65], v[92:93], v[64:65], v[4:5]
	v_pk_fma_f32 v[62:63], v[94:95], v[62:63], v[2:3]
	s_mov_b64 s[8:9], -1
	s_cbranch_vccnz .LBB0_1425
	v_cvt_pk_bf16_f32 v68, v62, v63
	v_cvt_pk_bf16_f32 v69, v64, v65
	s_mov_b64 s[8:9], 0
	global_store_dwordx2 v[66:67], v[68:69], off

.LBB0_1439:
	s_waitcnt vmcnt(7)
	s_nop 0
	v_pk_mul_f32 v[50:51], v[48:49], v[48:49]
	v_pk_mul_f32 v[52:53], v[46:47], v[46:47]
	s_waitcnt vmcnt(4)
	v_mul_f32_e32 v0, v34, v34
	v_pk_mov_b32 v[54:55], v[52:53], v[50:51] op_sel:[1,0]
	v_mov_b32_e32 v53, v51
	v_pk_add_f32 v[50:51], v[54:55], v[52:53]
	v_pk_mul_f32 v[52:53], v[44:45], v[44:45]
	v_pk_mul_f32 v[54:55], v[42:43], v[42:43]
	v_pk_add_f32 v[50:51], v[50:51], v[50:51] op_sel:[0,1] op_sel_hi:[1,0]
	v_pk_mov_b32 v[56:57], v[54:55], v[52:53] op_sel:[1,0]
	v_mov_b32_e32 v55, v53
	v_pk_add_f32 v[52:53], v[56:57], v[54:55]
	v_mul_f32_e32 v54, v35, v35
	v_pk_add_f32 v[52:53], v[52:53], v[52:53] op_sel:[0,1] op_sel_hi:[1,0]
	v_mov_b32_e32 v51, v0
	v_mov_b32_e32 v53, v54
	v_mul_f32_e32 v0, v39, v39
	v_mul_f32_e32 v55, v36, v36
	v_pk_add_f32 v[50:51], v[50:51], v[52:53]
	v_pk_fma_f32 v[52:53], v[38:39], v[38:39], v[0:1] op_sel_hi:[1,1,0]
	v_mul_f32_e32 v0, v41, v41
	v_mul_f32_e32 v56, v37, v37
	v_mov_b32_e32 v53, v55
	v_pk_fma_f32 v[54:55], v[40:41], v[40:41], v[0:1] op_sel_hi:[1,1,0]
	s_lshl_b64 s[22:23], s[22:23], 11
	v_mov_b32_e32 v55, v56
	v_pk_add_f32 v[52:53], v[52:53], v[54:55]
	s_and_b64 vcc, exec, s[6:7]
	v_pk_add_f32 v[50:51], v[50:51], v[52:53]
	s_nop 0
	v_add_f32_e32 v0, v50, v51
	s_nop 1
	v_add_f32_dpp v0, v0, v0 quad_perm:[1,0,3,2] row_mask:0xf bank_mask:0xf
	s_nop 1
	v_add_f32_dpp v0, v0, v0 quad_perm:[2,3,0,1] row_mask:0xf bank_mask:0xf
	s_nop 1
	v_add_f32_dpp v0, v0, v0 row_half_mirror row_mask:0xf bank_mask:0xf
	s_nop 1
	v_add_f32_dpp v0, v0, v0 row_mirror row_mask:0xf bank_mask:0xf
	v_mov_b32_e32 v50, v0
	s_nop 1
	v_permlane16_swap_b32 v50, v0
	s_nop 0
	v_add_f32_e32 v0, v50, v0
	v_mov_b32_e32 v50, v0
	s_nop 1
	v_permlane32_swap_b32 v50, v0
	s_nop 0
	v_add_f32_e32 v0, v50, v0
	v_fmamk_f32 v0, v0, 0x3a800000, v177
	v_mul_f32_e32 v50, 0x4b800000, v0
	v_cmp_gt_f32_e64 s[8:9], s52, v0
	s_nop 1
	v_cndmask_b32_e64 v0, v0, v50, s[8:9]
	v_rsq_f32_e32 v0, v0
	v_lshl_add_u64 v[50:51], v[86:87], 0, s[22:23]
	v_mul_f32_e32 v52, 0x45800000, v0
	v_cndmask_b32_e64 v54, v0, v52, s[8:9]
	v_pk_mul_f32 v[46:47], v[54:55], v[46:47] op_sel_hi:[0,1]
	v_pk_mul_f32 v[48:49], v[54:55], v[48:49] op_sel_hi:[0,1]
	v_pk_fma_f32 v[48:49], v[92:93], v[48:49], v[4:5]
	v_pk_fma_f32 v[46:47], v[94:95], v[46:47], v[2:3]
	s_mov_b64 s[8:9], -1
	s_cbranch_vccnz .LBB0_1441
	v_cvt_pk_bf16_f32 v52, v46, v47
	v_cvt_pk_bf16_f32 v53, v48, v49
	s_mov_b64 s[8:9], 0
	global_store_dwordx2 v[50:51], v[52:53], off

.LBB0_1455:
	s_waitcnt vmcnt(3)
	s_nop 0
	v_pk_mul_f32 v[34:35], v[32:33], v[32:33]
	v_pk_mul_f32 v[36:37], v[30:31], v[30:31]
	s_waitcnt vmcnt(0)
	v_mul_f32_e32 v0, v18, v18
	v_pk_mov_b32 v[38:39], v[36:37], v[34:35] op_sel:[1,0]
	v_mov_b32_e32 v37, v35
	v_pk_add_f32 v[34:35], v[38:39], v[36:37]
	v_pk_mul_f32 v[36:37], v[28:29], v[28:29]
	v_pk_mul_f32 v[38:39], v[26:27], v[26:27]
	v_pk_add_f32 v[34:35], v[34:35], v[34:35] op_sel:[0,1] op_sel_hi:[1,0]
	v_pk_mov_b32 v[40:41], v[38:39], v[36:37] op_sel:[1,0]
	v_mov_b32_e32 v39, v37
	v_pk_add_f32 v[36:37], v[40:41], v[38:39]
	v_mul_f32_e32 v38, v19, v19
	v_pk_add_f32 v[36:37], v[36:37], v[36:37] op_sel:[0,1] op_sel_hi:[1,0]
	v_mov_b32_e32 v35, v0
	v_mov_b32_e32 v37, v38
	v_mul_f32_e32 v0, v23, v23
	v_mul_f32_e32 v39, v20, v20
	v_pk_add_f32 v[34:35], v[34:35], v[36:37]
	v_pk_fma_f32 v[36:37], v[22:23], v[22:23], v[0:1] op_sel_hi:[1,1,0]
	v_mul_f32_e32 v0, v25, v25
	v_mul_f32_e32 v40, v21, v21
	v_mov_b32_e32 v37, v39
	v_pk_fma_f32 v[38:39], v[24:25], v[24:25], v[0:1] op_sel_hi:[1,1,0]
	s_lshl_b64 s[18:19], s[18:19], 11
	v_mov_b32_e32 v39, v40
	v_pk_add_f32 v[36:37], v[36:37], v[38:39]
	s_and_b64 vcc, exec, s[6:7]
	v_pk_add_f32 v[34:35], v[34:35], v[36:37]
	s_nop 0
	v_add_f32_e32 v0, v34, v35
	s_nop 1
	v_add_f32_dpp v0, v0, v0 quad_perm:[1,0,3,2] row_mask:0xf bank_mask:0xf
	s_nop 1
	v_add_f32_dpp v0, v0, v0 quad_perm:[2,3,0,1] row_mask:0xf bank_mask:0xf
	s_nop 1
	v_add_f32_dpp v0, v0, v0 row_half_mirror row_mask:0xf bank_mask:0xf
	s_nop 1
	v_add_f32_dpp v0, v0, v0 row_mirror row_mask:0xf bank_mask:0xf
	v_mov_b32_e32 v34, v0
	s_nop 1
	v_permlane16_swap_b32 v34, v0
	s_nop 0
	v_add_f32_e32 v0, v34, v0
	v_mov_b32_e32 v34, v0
	s_nop 1
	v_permlane32_swap_b32 v34, v0
	s_nop 0
	v_add_f32_e32 v0, v34, v0
	v_fmamk_f32 v0, v0, 0x3a800000, v177
	v_mul_f32_e32 v34, 0x4b800000, v0
	v_cmp_gt_f32_e64 s[8:9], s52, v0
	s_nop 1
	v_cndmask_b32_e64 v0, v0, v34, s[8:9]
	v_rsq_f32_e32 v0, v0
	v_lshl_add_u64 v[34:35], v[86:87], 0, s[18:19]
	v_mul_f32_e32 v36, 0x45800000, v0
	v_cndmask_b32_e64 v38, v0, v36, s[8:9]
	v_pk_mul_f32 v[30:31], v[38:39], v[30:31] op_sel_hi:[0,1]
	v_pk_mul_f32 v[32:33], v[38:39], v[32:33] op_sel_hi:[0,1]
	v_pk_fma_f32 v[32:33], v[92:93], v[32:33], v[4:5]
	v_pk_fma_f32 v[30:31], v[94:95], v[30:31], v[2:3]
	s_mov_b64 s[8:9], -1
	s_cbranch_vccnz .LBB0_1457
	v_cvt_pk_bf16_f32 v36, v30, v31
	v_cvt_pk_bf16_f32 v37, v32, v33
	s_mov_b64 s[8:9], 0
	global_store_dwordx2 v[34:35], v[36:37], off
